# phase 19 attention epilogue hand-rewritten: gate and subnorm-gain loads hoisted, counted vmcnt waits instead of 16 serialized vmcnt(0)
# speedup vs baseline: 1.0030x; 1.0030x over previous
; #define GAS __attribute__((address_space(1)))
;     ...
;         if (map == 0 && active) {
;             float ss = 0.f;
; #pragma unroll
;             for (int d = 0; d < 4; ++d)
; #pragma unroll
;                 for (int r = 0; r < 16; ++r) { const float v = o[d][r] * inv - xch[(sb * 64 + d * 16 + r) * 64 + lane]; o[d][r] = v; ss += v * v; }
;             ss += __shfl_xor(ss, 32);
;             const float rsn = rsqrtf(ss * (1.f / 128.f) + 1e-5f) * (1.f - lam_init);
;             const float* subg = F.a->in[14] + j * 128; const bf16* GA = (const bf16*)(F.ws + WS_GA) + (size_t)qrow * D + hcol; bf16* orow = OB + (size_t)qrow * D + hcol;
; #pragma unroll
;             for (int d = 0; d < 4; ++d)
; #pragma unroll
;                 for (int rg = 0; rg < 4; ++rg) { const int dc = d * 32 + 8 * rg + 4 * hi; const f32x4 sg = *(const GAS f32x4*)(subg + dc); const v2u gg = *(const GAS v2u*)(GA + dc);
.LBB0_3334:
	s_andn2_b64 vcc, exec, s[10:11]
	s_waitcnt vmcnt(0) lgkmcnt(0)
	s_barrier
	s_cbranch_vccnz .LBB0_3336
	v_lshl_add_u64 v[72:73], s[18:19], 0, v[172:173]
	s_lshl_b32 s6, s4, 1
	v_readlane_b32 s4, v254, 29
	v_lshl_add_u64 v[74:75], v[72:73], 0, s[6:7]
	v_readlane_b32 s5, v254, 30
	v_lshlrev_b32_e32 v162, 3, v187
	v_readlane_b32 s2, v254, 27
	v_lshl_add_u64 v[72:73], s[4:5], 0, v[172:173]
	v_lshl_add_u64 v[74:75], v[74:75], 0, v[162:163]
	v_readlane_b32 s3, v254, 28
	v_lshl_add_u64 v[88:89], v[72:73], 0, s[6:7]
	s_nop 0
	v_lshl_add_u64 v[88:89], v[88:89], 0, v[162:163]
	global_load_dwordx2 v[188:189], v[74:75], off
	global_load_dwordx2 v[190:191], v[74:75], off offset:16
	global_load_dwordx2 v[192:193], v[74:75], off offset:32
	global_load_dwordx2 v[194:195], v[74:75], off offset:48
	global_load_dwordx2 v[196:197], v[74:75], off offset:64
	global_load_dwordx2 v[198:199], v[74:75], off offset:80
	global_load_dwordx2 v[200:201], v[74:75], off offset:96
	global_load_dwordx2 v[202:203], v[74:75], off offset:112
	global_load_dwordx2 v[204:205], v[74:75], off offset:128
	global_load_dwordx2 v[206:207], v[74:75], off offset:144
	global_load_dwordx2 v[208:209], v[74:75], off offset:160
	global_load_dwordx2 v[210:211], v[74:75], off offset:176
	global_load_dwordx2 v[212:213], v[74:75], off offset:192
	global_load_dwordx2 v[214:215], v[74:75], off offset:208
	global_load_dwordx2 v[216:217], v[74:75], off offset:224
	global_load_dwordx2 v[218:219], v[74:75], off offset:240
	v_lshl_add_u32 v70, v186, 2, s73
	ds_read2st64_b32 v[92:93], v70 offset1:1
	ds_read2st64_b32 v[94:95], v70 offset0:2 offset1:3
	ds_read2st64_b32 v[96:97], v70 offset0:4 offset1:5
	ds_read2st64_b32 v[98:99], v70 offset0:6 offset1:7
	ds_read2st64_b32 v[100:101], v70 offset0:8 offset1:9
	ds_read2st64_b32 v[102:103], v70 offset0:10 offset1:11
	ds_read2st64_b32 v[104:105], v70 offset0:12 offset1:13
	ds_read2st64_b32 v[106:107], v70 offset0:14 offset1:15
	ds_read2st64_b32 v[108:109], v70 offset0:16 offset1:17
	ds_read2st64_b32 v[110:111], v70 offset0:18 offset1:19
	ds_read2st64_b32 v[112:113], v70 offset0:20 offset1:21
	ds_read2st64_b32 v[114:115], v70 offset0:22 offset1:23
	ds_read2st64_b32 v[116:117], v70 offset0:24 offset1:25
	ds_read2st64_b32 v[118:119], v70 offset0:26 offset1:27
	ds_read2st64_b32 v[120:121], v70 offset0:28 offset1:29
	ds_read2st64_b32 v[122:123], v70 offset0:30 offset1:31
	ds_read2st64_b32 v[124:125], v70 offset0:32 offset1:33
	ds_read2st64_b32 v[126:127], v70 offset0:34 offset1:35
	ds_read2st64_b32 v[128:129], v70 offset0:36 offset1:37
	ds_read2st64_b32 v[130:131], v70 offset0:38 offset1:39
	ds_read2st64_b32 v[132:133], v70 offset0:40 offset1:41
	ds_read2st64_b32 v[134:135], v70 offset0:42 offset1:43
	ds_read2st64_b32 v[136:137], v70 offset0:44 offset1:45
	ds_read2st64_b32 v[138:139], v70 offset0:46 offset1:47
	ds_read2st64_b32 v[140:141], v70 offset0:48 offset1:49
	ds_read2st64_b32 v[142:143], v70 offset0:50 offset1:51
	ds_read2st64_b32 v[144:145], v70 offset0:52 offset1:53
	ds_read2st64_b32 v[146:147], v70 offset0:54 offset1:55
	ds_read2st64_b32 v[148:149], v70 offset0:56 offset1:57
	ds_read2st64_b32 v[150:151], v70 offset0:58 offset1:59
	ds_read2st64_b32 v[152:153], v70 offset0:60 offset1:61
	ds_read2st64_b32 v[154:155], v70 offset0:62 offset1:63
	s_load_dwordx2 s[2:3], s[2:3], 0x70
	s_waitcnt lgkmcnt(0)
	v_pk_fma_f32 v[92:93], v[50:51], v[76:77], v[92:93] op_sel_hi:[1,0,1] neg_lo:[0,0,1] neg_hi:[0,0,1]
	v_pk_fma_f32 v[94:95], v[52:53], v[76:77], v[94:95] op_sel_hi:[1,0,1] neg_lo:[0,0,1] neg_hi:[0,0,1]
	v_pk_mul_f32 v[156:157], v[92:93], v[92:93]
	v_pk_mul_f32 v[160:161], v[94:95], v[94:95]
	global_load_dwordx4 v[50:53], v166, s[2:3] offset:512
	v_pk_fma_f32 v[96:97], v[54:55], v[76:77], v[96:97] op_sel_hi:[1,0,1] neg_lo:[0,0,1] neg_hi:[0,0,1]
	v_pk_fma_f32 v[98:99], v[56:57], v[76:77], v[98:99] op_sel_hi:[1,0,1] neg_lo:[0,0,1] neg_hi:[0,0,1]
	v_pk_mul_f32 v[174:175], v[96:97], v[96:97]
	v_pk_mul_f32 v[176:177], v[98:99], v[98:99]
	global_load_dwordx4 v[54:57], v166, s[2:3] offset:544
	v_pk_fma_f32 v[100:101], v[58:59], v[76:77], v[100:101] op_sel_hi:[1,0,1] neg_lo:[0,0,1] neg_hi:[0,0,1]
	v_pk_fma_f32 v[102:103], v[60:61], v[76:77], v[102:103] op_sel_hi:[1,0,1] neg_lo:[0,0,1] neg_hi:[0,0,1]
	v_pk_fma_f32 v[156:157], v[100:101], v[100:101], v[156:157]
	v_pk_fma_f32 v[160:161], v[102:103], v[102:103], v[160:161]
	global_load_dwordx4 v[58:61], v166, s[2:3] offset:576
	v_pk_fma_f32 v[104:105], v[62:63], v[76:77], v[104:105] op_sel_hi:[1,0,1] neg_lo:[0,0,1] neg_hi:[0,0,1]
	v_pk_fma_f32 v[106:107], v[64:65], v[76:77], v[106:107] op_sel_hi:[1,0,1] neg_lo:[0,0,1] neg_hi:[0,0,1]
	v_pk_fma_f32 v[174:175], v[104:105], v[104:105], v[174:175]
	v_pk_fma_f32 v[176:177], v[106:107], v[106:107], v[176:177]
	global_load_dwordx4 v[62:65], v166, s[2:3] offset:608
	v_pk_fma_f32 v[108:109], v[34:35], v[76:77], v[108:109] op_sel_hi:[1,0,1] neg_lo:[0,0,1] neg_hi:[0,0,1]
	v_pk_fma_f32 v[110:111], v[36:37], v[76:77], v[110:111] op_sel_hi:[1,0,1] neg_lo:[0,0,1] neg_hi:[0,0,1]
	v_pk_fma_f32 v[156:157], v[108:109], v[108:109], v[156:157]
	v_pk_fma_f32 v[160:161], v[110:111], v[110:111], v[160:161]
	global_load_dwordx4 v[34:37], v166, s[2:3] offset:640
	v_pk_fma_f32 v[112:113], v[38:39], v[76:77], v[112:113] op_sel_hi:[1,0,1] neg_lo:[0,0,1] neg_hi:[0,0,1]
	v_pk_fma_f32 v[114:115], v[40:41], v[76:77], v[114:115] op_sel_hi:[1,0,1] neg_lo:[0,0,1] neg_hi:[0,0,1]
	v_pk_fma_f32 v[174:175], v[112:113], v[112:113], v[174:175]
	v_pk_fma_f32 v[176:177], v[114:115], v[114:115], v[176:177]
	global_load_dwordx4 v[38:41], v166, s[2:3] offset:672
; #define GAS __attribute__((address_space(1)))
; __device__ __forceinline__ unsigned cvtpk(float lo, float hi) { typedef __bf16 b2 __attribute__((ext_vector_type(2))); f32x2 v = {lo, hi}; b2 b = __builtin_convertvector(v, b2); return __builtin_bit_cast(unsigned, b); }
;     ...
;                 for (int r = 0; r < 16; ++r) { const float v = o[d][r] * inv - xch[(sb * 64 + d * 16 + r) * 64 + lane]; o[d][r] = v; ss += v * v; }
;             ss += __shfl_xor(ss, 32);
;             const float rsn = rsqrtf(ss * (1.f / 128.f) + 1e-5f) * (1.f - lam_init);
;             const float* subg = F.a->in[14] + j * 128; const bf16* GA = (const bf16*)(F.ws + WS_GA) + (size_t)qrow * D + hcol; bf16* orow = OB + (size_t)qrow * D + hcol;
; #pragma unroll
;             for (int d = 0; d < 4; ++d)
; #pragma unroll
;                 for (int rg = 0; rg < 4; ++rg) { const int dc = d * 32 + 8 * rg + 4 * hi; const f32x4 sg = *(const GAS f32x4*)(subg + dc); const v2u gg = *(const GAS v2u*)(GA + dc);
;                     const float y0 = o[d][4 * rg + 0] * rsn * sg[0] * bf_lo(gg.x), y1 = o[d][4 * rg + 1] * rsn * sg[1] * bf_hi(gg.x), y2 = o[d][4 * rg + 2] * rsn * sg[2] * bf_lo(gg.y), y3 = o[d][4 * rg + 3] * rsn * sg[3] * bf_hi(gg.y);
;                     v2u wv; wv.x = cvtpk(y0, y1); wv.y = cvtpk(y2, y3); *(GAS v2u*)(orow + dc) = wv; }
	v_pk_fma_f32 v[116:117], v[42:43], v[76:77], v[116:117] op_sel_hi:[1,0,1] neg_lo:[0,0,1] neg_hi:[0,0,1]
	v_pk_fma_f32 v[118:119], v[44:45], v[76:77], v[118:119] op_sel_hi:[1,0,1] neg_lo:[0,0,1] neg_hi:[0,0,1]
	v_pk_fma_f32 v[156:157], v[116:117], v[116:117], v[156:157]
	v_pk_fma_f32 v[160:161], v[118:119], v[118:119], v[160:161]
	global_load_dwordx4 v[42:45], v166, s[2:3] offset:704
	v_pk_fma_f32 v[120:121], v[46:47], v[76:77], v[120:121] op_sel_hi:[1,0,1] neg_lo:[0,0,1] neg_hi:[0,0,1]
	v_pk_fma_f32 v[122:123], v[48:49], v[76:77], v[122:123] op_sel_hi:[1,0,1] neg_lo:[0,0,1] neg_hi:[0,0,1]
	v_pk_fma_f32 v[174:175], v[120:121], v[120:121], v[174:175]
	v_pk_fma_f32 v[176:177], v[122:123], v[122:123], v[176:177]
	global_load_dwordx4 v[46:49], v166, s[2:3] offset:736
	v_pk_fma_f32 v[124:125], v[18:19], v[76:77], v[124:125] op_sel_hi:[1,0,1] neg_lo:[0,0,1] neg_hi:[0,0,1]
	v_pk_fma_f32 v[126:127], v[20:21], v[76:77], v[126:127] op_sel_hi:[1,0,1] neg_lo:[0,0,1] neg_hi:[0,0,1]
	v_pk_fma_f32 v[156:157], v[124:125], v[124:125], v[156:157]
	v_pk_fma_f32 v[160:161], v[126:127], v[126:127], v[160:161]
	global_load_dwordx4 v[18:21], v166, s[2:3] offset:768
	v_pk_fma_f32 v[128:129], v[22:23], v[76:77], v[128:129] op_sel_hi:[1,0,1] neg_lo:[0,0,1] neg_hi:[0,0,1]
	v_pk_fma_f32 v[130:131], v[24:25], v[76:77], v[130:131] op_sel_hi:[1,0,1] neg_lo:[0,0,1] neg_hi:[0,0,1]
	v_pk_fma_f32 v[174:175], v[128:129], v[128:129], v[174:175]
	v_pk_fma_f32 v[176:177], v[130:131], v[130:131], v[176:177]
	global_load_dwordx4 v[22:25], v166, s[2:3] offset:800
	v_pk_fma_f32 v[132:133], v[26:27], v[76:77], v[132:133] op_sel_hi:[1,0,1] neg_lo:[0,0,1] neg_hi:[0,0,1]
	v_pk_fma_f32 v[134:135], v[28:29], v[76:77], v[134:135] op_sel_hi:[1,0,1] neg_lo:[0,0,1] neg_hi:[0,0,1]
	v_pk_fma_f32 v[156:157], v[132:133], v[132:133], v[156:157]
	v_pk_fma_f32 v[160:161], v[134:135], v[134:135], v[160:161]
	global_load_dwordx4 v[26:29], v166, s[2:3] offset:832
	v_pk_fma_f32 v[136:137], v[30:31], v[76:77], v[136:137] op_sel_hi:[1,0,1] neg_lo:[0,0,1] neg_hi:[0,0,1]
	v_pk_fma_f32 v[138:139], v[32:33], v[76:77], v[138:139] op_sel_hi:[1,0,1] neg_lo:[0,0,1] neg_hi:[0,0,1]
	v_pk_fma_f32 v[174:175], v[136:137], v[136:137], v[174:175]
	v_pk_fma_f32 v[176:177], v[138:139], v[138:139], v[176:177]
	global_load_dwordx4 v[30:33], v166, s[2:3] offset:864
	v_pk_fma_f32 v[140:141], v[2:3], v[76:77], v[140:141] op_sel_hi:[1,0,1] neg_lo:[0,0,1] neg_hi:[0,0,1]
	v_pk_fma_f32 v[142:143], v[4:5], v[76:77], v[142:143] op_sel_hi:[1,0,1] neg_lo:[0,0,1] neg_hi:[0,0,1]
	v_pk_fma_f32 v[156:157], v[140:141], v[140:141], v[156:157]
	v_pk_fma_f32 v[160:161], v[142:143], v[142:143], v[160:161]
	global_load_dwordx4 v[2:5], v166, s[2:3] offset:896
	v_pk_fma_f32 v[144:145], v[6:7], v[76:77], v[144:145] op_sel_hi:[1,0,1] neg_lo:[0,0,1] neg_hi:[0,0,1]
	v_pk_fma_f32 v[146:147], v[8:9], v[76:77], v[146:147] op_sel_hi:[1,0,1] neg_lo:[0,0,1] neg_hi:[0,0,1]
	v_pk_fma_f32 v[174:175], v[144:145], v[144:145], v[174:175]
	v_pk_fma_f32 v[176:177], v[146:147], v[146:147], v[176:177]
	global_load_dwordx4 v[6:9], v166, s[2:3] offset:928
	v_pk_fma_f32 v[148:149], v[10:11], v[76:77], v[148:149] op_sel_hi:[1,0,1] neg_lo:[0,0,1] neg_hi:[0,0,1]
	v_pk_fma_f32 v[150:151], v[12:13], v[76:77], v[150:151] op_sel_hi:[1,0,1] neg_lo:[0,0,1] neg_hi:[0,0,1]
	v_pk_fma_f32 v[156:157], v[148:149], v[148:149], v[156:157]
	v_pk_fma_f32 v[160:161], v[150:151], v[150:151], v[160:161]
	global_load_dwordx4 v[10:13], v166, s[2:3] offset:960
	v_pk_fma_f32 v[152:153], v[14:15], v[76:77], v[152:153] op_sel_hi:[1,0,1] neg_lo:[0,0,1] neg_hi:[0,0,1]
	v_pk_fma_f32 v[154:155], v[16:17], v[76:77], v[154:155] op_sel_hi:[1,0,1] neg_lo:[0,0,1] neg_hi:[0,0,1]
	v_pk_fma_f32 v[174:175], v[152:153], v[152:153], v[174:175]
	v_pk_fma_f32 v[176:177], v[154:155], v[154:155], v[176:177]
	global_load_dwordx4 v[14:17], v166, s[2:3] offset:992
	v_pk_add_f32 v[156:157], v[156:157], v[160:161]
	v_pk_add_f32 v[174:175], v[174:175], v[176:177]
	s_nop 0
	v_pk_add_f32 v[156:157], v[156:157], v[174:175]
	s_nop 0
	v_add_f32_e32 v78, v156, v157
	s_mov_b32 s4, 0x800000
	ds_bpermute_b32 v79, v158, v78
	s_waitcnt lgkmcnt(0)
	v_add_f32_e32 v78, v78, v79
	v_fmamk_f32 v78, v78, 0x3c000000, v185
	v_mul_f32_e32 v79, 0x4b800000, v78
	v_cmp_gt_f32_e32 vcc, s4, v78
	s_nop 1
	v_cndmask_b32_e32 v78, v78, v79, vcc
	v_rsq_f32_e32 v79, v78
	s_nop 1
	v_mul_f32_e32 v90, 0x45800000, v79
	v_cndmask_b32_e32 v90, v79, v90, vcc
	v_mul_f32_e32 v90, 0x3ee34c56, v90
	s_waitcnt vmcnt(15)
	v_lshlrev_b32_e32 v80, 16, v188
	v_and_b32_e32 v81, 0xffff0000, v188
	v_lshlrev_b32_e32 v82, 16, v189
	v_and_b32_e32 v83, 0xffff0000, v189
	v_pk_mul_f32 v[92:93], v[92:93], v[90:91] op_sel_hi:[1,0]
	v_pk_mul_f32 v[94:95], v[94:95], v[90:91] op_sel_hi:[1,0]
	v_pk_mul_f32 v[92:93], v[50:51], v[92:93]
	v_pk_mul_f32 v[94:95], v[52:53], v[94:95]
	v_pk_mul_f32 v[92:93], v[92:93], v[80:81]
	v_pk_mul_f32 v[94:95], v[94:95], v[82:83]
	v_cvt_pk_bf16_f32 v92, v92, v93
	v_cvt_pk_bf16_f32 v93, v94, v95
	global_store_dwordx2 v[88:89], v[92:93], off
	s_waitcnt vmcnt(15)
	v_lshlrev_b32_e32 v84, 16, v190
	v_and_b32_e32 v85, 0xffff0000, v190
	v_lshlrev_b32_e32 v86, 16, v191
	v_and_b32_e32 v87, 0xffff0000, v191
	v_pk_mul_f32 v[96:97], v[96:97], v[90:91] op_sel_hi:[1,0]
	v_pk_mul_f32 v[98:99], v[98:99], v[90:91] op_sel_hi:[1,0]
	v_pk_mul_f32 v[96:97], v[54:55], v[96:97]
	v_pk_mul_f32 v[98:99], v[56:57], v[98:99]
	v_pk_mul_f32 v[96:97], v[96:97], v[84:85]
	v_pk_mul_f32 v[98:99], v[98:99], v[86:87]
	v_cvt_pk_bf16_f32 v96, v96, v97
	v_cvt_pk_bf16_f32 v97, v98, v99
	global_store_dwordx2 v[88:89], v[96:97], off offset:16
	s_waitcnt vmcnt(15)
; #define GAS __attribute__((address_space(1)))
; __device__ __forceinline__ unsigned cvtpk(float lo, float hi) { typedef __bf16 b2 __attribute__((ext_vector_type(2))); f32x2 v = {lo, hi}; b2 b = __builtin_convertvector(v, b2); return __builtin_bit_cast(unsigned, b); }
;     ...
;             for (int d = 0; d < 4; ++d)
; #pragma unroll
;                 for (int rg = 0; rg < 4; ++rg) { const int dc = d * 32 + 8 * rg + 4 * hi; const f32x4 sg = *(const GAS f32x4*)(subg + dc); const v2u gg = *(const GAS v2u*)(GA + dc);
;                     const float y0 = o[d][4 * rg + 0] * rsn * sg[0] * bf_lo(gg.x), y1 = o[d][4 * rg + 1] * rsn * sg[1] * bf_hi(gg.x), y2 = o[d][4 * rg + 2] * rsn * sg[2] * bf_lo(gg.y), y3 = o[d][4 * rg + 3] * rsn * sg[3] * bf_hi(gg.y);
;                     v2u wv; wv.x = cvtpk(y0, y1); wv.y = cvtpk(y2, y3); *(GAS v2u*)(orow + dc) = wv; }
	v_lshlrev_b32_e32 v80, 16, v192
	v_and_b32_e32 v81, 0xffff0000, v192
	v_lshlrev_b32_e32 v82, 16, v193
	v_and_b32_e32 v83, 0xffff0000, v193
	v_pk_mul_f32 v[100:101], v[100:101], v[90:91] op_sel_hi:[1,0]
	v_pk_mul_f32 v[102:103], v[102:103], v[90:91] op_sel_hi:[1,0]
	v_pk_mul_f32 v[100:101], v[58:59], v[100:101]
	v_pk_mul_f32 v[102:103], v[60:61], v[102:103]
	v_pk_mul_f32 v[100:101], v[100:101], v[80:81]
	v_pk_mul_f32 v[102:103], v[102:103], v[82:83]
	v_cvt_pk_bf16_f32 v100, v100, v101
	v_cvt_pk_bf16_f32 v101, v102, v103
	global_store_dwordx2 v[88:89], v[100:101], off offset:32
	s_waitcnt vmcnt(15)
	v_lshlrev_b32_e32 v84, 16, v194
	v_and_b32_e32 v85, 0xffff0000, v194
	v_lshlrev_b32_e32 v86, 16, v195
	v_and_b32_e32 v87, 0xffff0000, v195
	v_pk_mul_f32 v[104:105], v[104:105], v[90:91] op_sel_hi:[1,0]
	v_pk_mul_f32 v[106:107], v[106:107], v[90:91] op_sel_hi:[1,0]
	v_pk_mul_f32 v[104:105], v[62:63], v[104:105]
	v_pk_mul_f32 v[106:107], v[64:65], v[106:107]
	v_pk_mul_f32 v[104:105], v[104:105], v[84:85]
	v_pk_mul_f32 v[106:107], v[106:107], v[86:87]
	v_cvt_pk_bf16_f32 v104, v104, v105
	v_cvt_pk_bf16_f32 v105, v106, v107
	global_store_dwordx2 v[88:89], v[104:105], off offset:48
	s_waitcnt vmcnt(15)
	v_lshlrev_b32_e32 v80, 16, v196
	v_and_b32_e32 v81, 0xffff0000, v196
	v_lshlrev_b32_e32 v82, 16, v197
	v_and_b32_e32 v83, 0xffff0000, v197
	v_pk_mul_f32 v[108:109], v[108:109], v[90:91] op_sel_hi:[1,0]
	v_pk_mul_f32 v[110:111], v[110:111], v[90:91] op_sel_hi:[1,0]
	v_pk_mul_f32 v[108:109], v[34:35], v[108:109]
	v_pk_mul_f32 v[110:111], v[36:37], v[110:111]
	v_pk_mul_f32 v[108:109], v[108:109], v[80:81]
	v_pk_mul_f32 v[110:111], v[110:111], v[82:83]
	v_cvt_pk_bf16_f32 v108, v108, v109
	v_cvt_pk_bf16_f32 v109, v110, v111
	global_store_dwordx2 v[88:89], v[108:109], off offset:64
	s_waitcnt vmcnt(15)
	v_lshlrev_b32_e32 v84, 16, v198
	v_and_b32_e32 v85, 0xffff0000, v198
	v_lshlrev_b32_e32 v86, 16, v199
	v_and_b32_e32 v87, 0xffff0000, v199
	v_pk_mul_f32 v[112:113], v[112:113], v[90:91] op_sel_hi:[1,0]
	v_pk_mul_f32 v[114:115], v[114:115], v[90:91] op_sel_hi:[1,0]
	v_pk_mul_f32 v[112:113], v[38:39], v[112:113]
	v_pk_mul_f32 v[114:115], v[40:41], v[114:115]
	v_pk_mul_f32 v[112:113], v[112:113], v[84:85]
	v_pk_mul_f32 v[114:115], v[114:115], v[86:87]
	v_cvt_pk_bf16_f32 v112, v112, v113
	v_cvt_pk_bf16_f32 v113, v114, v115
	global_store_dwordx2 v[88:89], v[112:113], off offset:80
	s_waitcnt vmcnt(15)
	v_lshlrev_b32_e32 v80, 16, v200
	v_and_b32_e32 v81, 0xffff0000, v200
	v_lshlrev_b32_e32 v82, 16, v201
	v_and_b32_e32 v83, 0xffff0000, v201
	v_pk_mul_f32 v[116:117], v[116:117], v[90:91] op_sel_hi:[1,0]
	v_pk_mul_f32 v[118:119], v[118:119], v[90:91] op_sel_hi:[1,0]
	v_pk_mul_f32 v[116:117], v[42:43], v[116:117]
	v_pk_mul_f32 v[118:119], v[44:45], v[118:119]
	v_pk_mul_f32 v[116:117], v[116:117], v[80:81]
	v_pk_mul_f32 v[118:119], v[118:119], v[82:83]
	v_cvt_pk_bf16_f32 v116, v116, v117
	v_cvt_pk_bf16_f32 v117, v118, v119
	global_store_dwordx2 v[88:89], v[116:117], off offset:96
	s_waitcnt vmcnt(15)
	v_lshlrev_b32_e32 v84, 16, v202
	v_and_b32_e32 v85, 0xffff0000, v202
	v_lshlrev_b32_e32 v86, 16, v203
	v_and_b32_e32 v87, 0xffff0000, v203
	v_pk_mul_f32 v[120:121], v[120:121], v[90:91] op_sel_hi:[1,0]
	v_pk_mul_f32 v[122:123], v[122:123], v[90:91] op_sel_hi:[1,0]
	v_pk_mul_f32 v[120:121], v[46:47], v[120:121]
	v_pk_mul_f32 v[122:123], v[48:49], v[122:123]
	v_pk_mul_f32 v[120:121], v[120:121], v[84:85]
	v_pk_mul_f32 v[122:123], v[122:123], v[86:87]
	v_cvt_pk_bf16_f32 v120, v120, v121
	v_cvt_pk_bf16_f32 v121, v122, v123
	global_store_dwordx2 v[88:89], v[120:121], off offset:112
	s_waitcnt vmcnt(15)
	v_lshlrev_b32_e32 v80, 16, v204
	v_and_b32_e32 v81, 0xffff0000, v204
	v_lshlrev_b32_e32 v82, 16, v205
	v_and_b32_e32 v83, 0xffff0000, v205
	v_pk_mul_f32 v[124:125], v[124:125], v[90:91] op_sel_hi:[1,0]
	v_pk_mul_f32 v[126:127], v[126:127], v[90:91] op_sel_hi:[1,0]
	v_pk_mul_f32 v[124:125], v[18:19], v[124:125]
	v_pk_mul_f32 v[126:127], v[20:21], v[126:127]
	v_pk_mul_f32 v[124:125], v[124:125], v[80:81]
	v_pk_mul_f32 v[126:127], v[126:127], v[82:83]
	v_cvt_pk_bf16_f32 v124, v124, v125
	v_cvt_pk_bf16_f32 v125, v126, v127
	global_store_dwordx2 v[88:89], v[124:125], off offset:128
	s_waitcnt vmcnt(15)
; #define GAS __attribute__((address_space(1)))
; __device__ __forceinline__ unsigned cvtpk(float lo, float hi) { typedef __bf16 b2 __attribute__((ext_vector_type(2))); f32x2 v = {lo, hi}; b2 b = __builtin_convertvector(v, b2); return __builtin_bit_cast(unsigned, b); }
;     ...
;             for (int d = 0; d < 4; ++d)
; #pragma unroll
;                 for (int rg = 0; rg < 4; ++rg) { const int dc = d * 32 + 8 * rg + 4 * hi; const f32x4 sg = *(const GAS f32x4*)(subg + dc); const v2u gg = *(const GAS v2u*)(GA + dc);
;                     const float y0 = o[d][4 * rg + 0] * rsn * sg[0] * bf_lo(gg.x), y1 = o[d][4 * rg + 1] * rsn * sg[1] * bf_hi(gg.x), y2 = o[d][4 * rg + 2] * rsn * sg[2] * bf_lo(gg.y), y3 = o[d][4 * rg + 3] * rsn * sg[3] * bf_hi(gg.y);
;                     v2u wv; wv.x = cvtpk(y0, y1); wv.y = cvtpk(y2, y3); *(GAS v2u*)(orow + dc) = wv; }
	v_lshlrev_b32_e32 v84, 16, v206
	v_and_b32_e32 v85, 0xffff0000, v206
	v_lshlrev_b32_e32 v86, 16, v207
	v_and_b32_e32 v87, 0xffff0000, v207
	v_pk_mul_f32 v[128:129], v[128:129], v[90:91] op_sel_hi:[1,0]
	v_pk_mul_f32 v[130:131], v[130:131], v[90:91] op_sel_hi:[1,0]
	v_pk_mul_f32 v[128:129], v[22:23], v[128:129]
	v_pk_mul_f32 v[130:131], v[24:25], v[130:131]
	v_pk_mul_f32 v[128:129], v[128:129], v[84:85]
	v_pk_mul_f32 v[130:131], v[130:131], v[86:87]
	v_cvt_pk_bf16_f32 v128, v128, v129
	v_cvt_pk_bf16_f32 v129, v130, v131
	global_store_dwordx2 v[88:89], v[128:129], off offset:144
	s_waitcnt vmcnt(15)
	v_lshlrev_b32_e32 v80, 16, v208
	v_and_b32_e32 v81, 0xffff0000, v208
	v_lshlrev_b32_e32 v82, 16, v209
	v_and_b32_e32 v83, 0xffff0000, v209
	v_pk_mul_f32 v[132:133], v[132:133], v[90:91] op_sel_hi:[1,0]
	v_pk_mul_f32 v[134:135], v[134:135], v[90:91] op_sel_hi:[1,0]
	v_pk_mul_f32 v[132:133], v[26:27], v[132:133]
	v_pk_mul_f32 v[134:135], v[28:29], v[134:135]
	v_pk_mul_f32 v[132:133], v[132:133], v[80:81]
	v_pk_mul_f32 v[134:135], v[134:135], v[82:83]
	v_cvt_pk_bf16_f32 v132, v132, v133
	v_cvt_pk_bf16_f32 v133, v134, v135
	global_store_dwordx2 v[88:89], v[132:133], off offset:160
	s_waitcnt vmcnt(15)
	v_lshlrev_b32_e32 v84, 16, v210
	v_and_b32_e32 v85, 0xffff0000, v210
	v_lshlrev_b32_e32 v86, 16, v211
	v_and_b32_e32 v87, 0xffff0000, v211
	v_pk_mul_f32 v[136:137], v[136:137], v[90:91] op_sel_hi:[1,0]
	v_pk_mul_f32 v[138:139], v[138:139], v[90:91] op_sel_hi:[1,0]
	v_pk_mul_f32 v[136:137], v[30:31], v[136:137]
	v_pk_mul_f32 v[138:139], v[32:33], v[138:139]
	v_pk_mul_f32 v[136:137], v[136:137], v[84:85]
	v_pk_mul_f32 v[138:139], v[138:139], v[86:87]
	v_cvt_pk_bf16_f32 v136, v136, v137
	v_cvt_pk_bf16_f32 v137, v138, v139
	global_store_dwordx2 v[88:89], v[136:137], off offset:176
	s_waitcnt vmcnt(15)
	v_lshlrev_b32_e32 v80, 16, v212
	v_and_b32_e32 v81, 0xffff0000, v212
	v_lshlrev_b32_e32 v82, 16, v213
	v_and_b32_e32 v83, 0xffff0000, v213
	v_pk_mul_f32 v[140:141], v[140:141], v[90:91] op_sel_hi:[1,0]
	v_pk_mul_f32 v[142:143], v[142:143], v[90:91] op_sel_hi:[1,0]
	v_pk_mul_f32 v[140:141], v[2:3], v[140:141]
	v_pk_mul_f32 v[142:143], v[4:5], v[142:143]
	v_pk_mul_f32 v[140:141], v[140:141], v[80:81]
	v_pk_mul_f32 v[142:143], v[142:143], v[82:83]
	v_cvt_pk_bf16_f32 v140, v140, v141
	v_cvt_pk_bf16_f32 v141, v142, v143
	global_store_dwordx2 v[88:89], v[140:141], off offset:192
	s_waitcnt vmcnt(15)
	v_lshlrev_b32_e32 v84, 16, v214
	v_and_b32_e32 v85, 0xffff0000, v214
	v_lshlrev_b32_e32 v86, 16, v215
	v_and_b32_e32 v87, 0xffff0000, v215
	v_pk_mul_f32 v[144:145], v[144:145], v[90:91] op_sel_hi:[1,0]
	v_pk_mul_f32 v[146:147], v[146:147], v[90:91] op_sel_hi:[1,0]
	v_pk_mul_f32 v[144:145], v[6:7], v[144:145]
	v_pk_mul_f32 v[146:147], v[8:9], v[146:147]
	v_pk_mul_f32 v[144:145], v[144:145], v[84:85]
	v_pk_mul_f32 v[146:147], v[146:147], v[86:87]
	v_cvt_pk_bf16_f32 v144, v144, v145
	v_cvt_pk_bf16_f32 v145, v146, v147
	global_store_dwordx2 v[88:89], v[144:145], off offset:208
	s_waitcnt vmcnt(15)
	v_lshlrev_b32_e32 v80, 16, v216
	v_and_b32_e32 v81, 0xffff0000, v216
	v_lshlrev_b32_e32 v82, 16, v217
	v_and_b32_e32 v83, 0xffff0000, v217
	v_pk_mul_f32 v[148:149], v[148:149], v[90:91] op_sel_hi:[1,0]
	v_pk_mul_f32 v[150:151], v[150:151], v[90:91] op_sel_hi:[1,0]
	v_pk_mul_f32 v[148:149], v[10:11], v[148:149]
	v_pk_mul_f32 v[150:151], v[12:13], v[150:151]
	v_pk_mul_f32 v[148:149], v[148:149], v[80:81]
	v_pk_mul_f32 v[150:151], v[150:151], v[82:83]
	v_cvt_pk_bf16_f32 v148, v148, v149
	v_cvt_pk_bf16_f32 v149, v150, v151
	global_store_dwordx2 v[88:89], v[148:149], off offset:224
	s_waitcnt vmcnt(15)
	v_lshlrev_b32_e32 v84, 16, v218
	v_and_b32_e32 v85, 0xffff0000, v218
	v_lshlrev_b32_e32 v86, 16, v219
	v_and_b32_e32 v87, 0xffff0000, v219
	v_pk_mul_f32 v[152:153], v[152:153], v[90:91] op_sel_hi:[1,0]
	v_pk_mul_f32 v[154:155], v[154:155], v[90:91] op_sel_hi:[1,0]
	v_pk_mul_f32 v[152:153], v[14:15], v[152:153]
	v_pk_mul_f32 v[154:155], v[16:17], v[154:155]
	v_pk_mul_f32 v[152:153], v[152:153], v[84:85]
	v_pk_mul_f32 v[154:155], v[154:155], v[86:87]
	v_cvt_pk_bf16_f32 v152, v152, v153
	v_cvt_pk_bf16_f32 v153, v154, v155
	global_store_dwordx2 v[88:89], v[152:153], off offset:240
